# P4: next item's chunk-0 gather issued during the current item's epilogue (idx hand-over through LDS scratch), on top of final
# speedup vs baseline: 1.0031x; 1.0031x over previous
; #define LAS __attribute__((address_space(3)))
; __device__ __forceinline__ unsigned cvt_pk_bf16(float lo, float hi) { unsigned r; asm("v_cvt_pk_bf16_f32 %0, %1, %2" : "=v"(r) : "v"(lo), "v"(hi)); return r; }
; __device__ __forceinline__ void p4_attn(const Params& p, unsigned char* lds, int bid, int nb, bool dry) {
;     ...
;   LAS unsigned* pcnt = (LAS unsigned*)((LAS unsigned char*)lds + 2 * CBUF + 129 * 32 * 4 + 2048) + (wid >> 1);
;   if (tid < 4) ((LAS unsigned*)((LAS unsigned char*)lds + 2 * CBUF + 129 * 32 * 4 + 2048))[tid] = 0u;
;   __syncthreads();
;   unsigned epoch = 0u;
;   const int tok = wid >> 1, hw = wid & 1, head = hw * 16 + r16;
;   const float SC = 0.08838834764831845f * LOG2E;
;   const int qoff = 16 * (g ^ (r16 >> 3));
;   const int q4 = r16 >> 2, pp = r16 & 3;
;   const int troff = (4 * g + q4) * CROW + 16 * ((pp >> 1) ^ (g >> 1)) + 8 * (pp & 1);
;   const int wrow = 16 * hw + 8 * (lane >> 5), wch = lane & 31;
;   for (int round = 0; round * nb < T / 4; ++round) {
;     const int item = round * nb + (bid + round * 37) % nb;
;     const int tg0 = item * 4, b = tg0 >> 11, t0 = tg0 & 2047, t = t0 + tok, tg = tg0 + tok;
;     const int nk = min(t + 1, 256), nkmax = min(t0 + 4, 256), nch = (nkmax + 31) >> 5;
;     ((LAS unsigned*)idxs)[tid] = ((const unsigned*)(idxg + (size_t)tg0 * 256))[tid];
;     unsigned char* qrow = QL + (size_t)tg * 8192 + head * 256;
;     bf16x8 qB[8];
; #pragma unroll
;     for (int s = 0; s < 8; ++s) { const u32x2 qw = *(const u32x2*)(qrow + 32 * s + 8 * g);
;       typedef float f32x2v __attribute__((ext_vector_type(2)));
;       const f32x2v a0 = __builtin_amdgcn_cvt_pk_f32_fp8(qw[0], false), a1 = __builtin_amdgcn_cvt_pk_f32_fp8(qw[0], true), a2 = __builtin_amdgcn_cvt_pk_f32_fp8(qw[1], false), a3 = __builtin_amdgcn_cvt_pk_f32_fp8(qw[1], true);
;       u32x4 pw; pw[0] = cvt_pk_bf16(a0[0], a0[1]); pw[1] = cvt_pk_bf16(a1[0], a1[1]); pw[2] = cvt_pk_bf16(a2[0], a2[1]); pw[3] = cvt_pk_bf16(a3[0], a3[1]);
;       union { u32x4 u; bf16x8 v; } cv; cv.u = pw; qB[s] = cv.v; }
.LBB0_988:
	s_or_b64 exec, exec, s[4:5]
	v_cmp_gt_i32_e32 vcc, 4, v2
	s_and_saveexec_b64 s[4:5], vcc
	v_add_u32_e32 v0, 0x26880, v0
	v_mov_b32_e32 v1, 0
	ds_write_b32 v0, v1
	s_or_b64 exec, exec, s[4:5]
	v_bfe_u32 v5, v2, 4, 2
	v_bfe_u32 v0, v2, 3, 1
	v_mov_b32_e32 v0, v5
	v_lshlrev_b32_e32 v162, 4, v0
	v_bfe_u32 v0, v2, 2, 2
	v_lshlrev_b32_e32 v148, 2, v5
	v_or_b32_e32 v0, v148, v0
	s_ashr_i32 s0, s3, 7
	s_lshr_b32 s3, s3, 2
	v_mul_u32_u24_e32 v163, 0x220, v0
	v_lshrrev_b32_e32 v0, 1, v2
	v_bfe_u32 v8, v2, 5, 1
	v_and_b32_e32 v6, 15, v2
	s_and_b32 s3, s3, 16
	v_and_b32_e32 v0, 1, v0
	v_readlane_b32 s4, v254, 36
	v_or_b32_e32 v7, s3, v6
	v_lshlrev_b32_e32 v164, 4, v0
	v_lshlrev_b32_e32 v0, 3, v2
	v_ashrrev_i32_e32 v3, 31, v2
	v_readlane_b32 s5, v254, 37
	v_and_b32_e32 v165, 8, v0
	v_and_b32_e32 v10, 31, v2
	v_lshl_add_u64 v[150:151], v[2:3], 2, s[4:5]
	v_lshlrev_b32_e32 v0, 8, v7
	v_mov_b32_e32 v1, 0
	v_readlane_b32 s4, v254, 42
	v_lshl_add_u64 v[152:153], s[92:93], 0, v[0:1]
	v_lshlrev_b32_e32 v0, 4, v10
	v_readlane_b32 s5, v254, 43
	v_lshl_or_b32 v9, v8, 3, s3
	s_add_i32 s3, 0, 0x26080
	v_lshl_add_u64 v[156:157], s[4:5], 0, v[0:1]
	s_lshl_b32 s4, s0, 9
	s_lshl_b32 s2, s0, 2
	v_lshl_add_u32 v166, v2, 2, s3
	s_add_i32 s3, s3, s4
	s_mul_i32 s4, s0, 0x4400
	v_and_b32_e32 v0, 31, v2
	s_add_i32 s2, s2, 0
	v_and_b32_e32 v4, 63, v2
	s_add_i32 s5, s4, 0
	v_lshlrev_b32_e32 v0, 4, v0
	s_add_i32 s4, 0, 0x22000
	v_mul_u32_u24_e32 v2, 0x220, v9
	s_mov_b32 s1, 0
	s_add_i32 s2, s2, 0x26880
	v_lshlrev_b32_e32 v154, 3, v5
	v_mov_b32_e32 v155, v1
	v_cmp_eq_u32_e64 s[8:9], 0, v4
	v_lshl_add_u32 v167, v9, 1, s3
	v_mul_u32_u24_e32 v168, 0x220, v6
	v_lshl_add_u32 v169, v7, 2, s4
	v_mov_b32_e32 v149, v1
	v_add3_u32 v170, s5, v0, v2
	s_movk_i32 s16, 0x80
	s_mov_b32 s4, 0x3e0293ee
	s_mov_b32 s17, 0xf149f2ca
	s_mov_b32 s18, 0x41800000
	v_mov_b32_e32 v171, 9
	v_mov_b32_e32 v172, 0x80
	v_mov_b32_e32 v173, 0xf149f2ca
	s_mov_b32 s10, 0
	s_mov_b32 s19, 0
	s_mov_b32 s20, 0
	s_lshl_b32 s28, s88, 11
	s_mov_b32 s29, 0
	v_lshl_add_u64 v[2:3], v[150:151], 0, s[28:29]
	global_load_dword v255, v[2:3], off
	s_lshl_b32 s28, s88, 2
	s_add_i32 s28, s28, s0
	s_lshl_b32 s28, s28, 13
	v_lshl_add_u64 v[194:195], v[152:153], 0, s[28:29]
	v_lshl_add_u64 v[194:195], v[194:195], 0, v[154:155]
	global_load_dwordx2 v[218:219], v[194:195], off
	global_load_dwordx2 v[220:221], v[194:195], off offset:32
	global_load_dwordx2 v[222:223], v[194:195], off offset:64
	global_load_dwordx2 v[224:225], v[194:195], off offset:96
	global_load_dwordx2 v[226:227], v[194:195], off offset:128
	global_load_dwordx2 v[228:229], v[194:195], off offset:160
	global_load_dwordx2 v[230:231], v[194:195], off offset:192
	global_load_dwordx2 v[232:233], v[194:195], off offset:224
	s_waitcnt vmcnt(0)
	s_lshl_b32 s42, s0, 6
	s_add_i32 s42, s42, 0x26890
	s_sub_i32 s44, s42, s3
	v_and_b32_e32 v2, 0x7f, v200
	v_cmp_gt_u32_e64 s[40:41], 16, v2
	s_waitcnt lgkmcnt(0)
	s_barrier
.LBB0_991:
	s_mul_i32 s11, s20, 37
	s_add_i32 s11, s11, s88
	s_ashr_i32 s12, s11, 31
	s_abs_i32 s11, s11
	v_readlane_b32 s13, v254, 32
	s_mul_hi_u32 s13, s11, s13
	v_readlane_b32 s14, v254, 33
	s_mul_i32 s13, s13, s14
	s_sub_i32 s11, s11, s13
	s_sub_i32 s13, s11, s14
	s_cmp_ge_u32 s11, s14
	s_cselect_b32 s11, s13, s11
	s_sub_i32 s13, s11, s14
	s_cmp_ge_u32 s11, s14
	s_cselect_b32 s11, s13, s11
	s_xor_b32 s11, s11, s12
	s_sub_i32 s22, s11, s12
	s_add_i32 s21, s22, s10
	s_lshl_b32 s10, s21, 2
	s_add_i32 s12, s10, s0
	s_ashr_i32 s11, s10, 31
	s_ashr_i32 s13, s12, 31
	s_lshl_b64 s[14:15], s[10:11], 9
	s_lshl_b64 s[12:13], s[12:13], 13
	v_lshl_add_u64 v[158:159], v[152:153], 0, s[12:13]
	s_waitcnt vmcnt(20)
	ds_write_b32 v166, v255
	s_and_saveexec_b64 s[12:13], s[8:9]
	s_cbranch_execz .LBB0_994
	s_mov_b64 s[14:15], exec
	v_mbcnt_lo_u32_b32 v0, s14, 0
	v_mbcnt_hi_u32_b32 v0, s15, v0
	v_cmp_eq_u32_e32 vcc, 0, v0
	s_and_b64 s[24:25], exec, vcc
	s_mov_b64 exec, s[24:25]
	s_bcnt1_i32_b64 s11, s[14:15]
	v_mov_b32_e32 v0, s2
	v_mov_b32_e32 v2, s11
	ds_add_u32 v0, v2

; #define LAS __attribute__((address_space(3)))
; __device__ __forceinline__ unsigned cvt_pk_bf16(float lo, float hi) { unsigned r; asm("v_cvt_pk_bf16_f32 %0, %1, %2" : "=v"(r) : "v"(lo), "v"(hi)); return r; }
; #define P4_LOAD(ch) do { const u32x4 kk_ = *(const LAS u32x4*)(idxs + tok * 256 + (ch) * 32 + wrow); \
;       _Pragma("unroll") for (int i = 0; i < 8; ++i) { \
;       const int key = (int)((kk_[i >> 1] >> (16 * (i & 1))) & 0xffffu); stg[i] = *(const u32x4*)(cbase + (size_t)key * 256); } } while (0)
; #define P4_WRITE(bufp) do { _Pragma("unroll") for (int i = 0; i < 8; ++i) \
;       *(LAS u32x4*)((bufp) + (wrow + i) * CROW + 16 * (wch ^ (lane >> 5))) = stg[i]; } while (0)
; __device__ __forceinline__ void p4_attn(const Params& p, unsigned char* lds, int bid, int nb, bool dry) {
;     ...
;     ((LAS unsigned*)idxs)[tid] = ((const unsigned*)(idxg + (size_t)tg0 * 256))[tid];
;     unsigned char* qrow = QL + (size_t)tg * 8192 + head * 256;
;     bf16x8 qB[8];
; #pragma unroll
;     for (int s = 0; s < 8; ++s) { const u32x2 qw = *(const u32x2*)(qrow + 32 * s + 8 * g);
;       typedef float f32x2v __attribute__((ext_vector_type(2)));
;       const f32x2v a0 = __builtin_amdgcn_cvt_pk_f32_fp8(qw[0], false), a1 = __builtin_amdgcn_cvt_pk_f32_fp8(qw[0], true), a2 = __builtin_amdgcn_cvt_pk_f32_fp8(qw[1], false), a3 = __builtin_amdgcn_cvt_pk_f32_fp8(qw[1], true);
;       u32x4 pw; pw[0] = cvt_pk_bf16(a0[0], a0[1]); pw[1] = cvt_pk_bf16(a1[0], a1[1]); pw[2] = cvt_pk_bf16(a2[0], a2[1]); pw[3] = cvt_pk_bf16(a3[0], a3[1]);
;       union { u32x4 u; bf16x8 v; } cv; cv.u = pw; qB[s] = cv.v; }
;     epoch += 2u; pair_sync(pcnt, epoch, lane);
;     u32x4 stg[8];
;     const bf16_t* cbase = ckvn + (size_t)b * L * 256 + wch * 8;
;     ...
;     P4_LOAD(0);
;     P4_WRITE(cbuf + tok * CTOK);
;     if (nch > 1) P4_LOAD(1);
.LBB0_996:
	s_ashr_i32 s12, s21, 9
	s_ashr_i32 s13, s12, 31
	s_lshl_b64 s[12:13], s[12:13], 20
	v_lshl_add_u64 v[160:161], v[156:157], 0, s[12:13]
	s_cmp_lg_u32 s20, 0
	s_cbranch_scc1 .Lp4_skip0
	ds_read_b128 v[36:39], v167
	s_waitcnt lgkmcnt(0)
	v_lshlrev_b32_e32 v0, 9, v36
	v_and_b32_e32 v0, 0x1fffe00, v0
	v_lshl_add_u64 v[2:3], v[160:161], 0, v[0:1]
	v_lshlrev_b32_sdwa v0, v171, v36 dst_sel:DWORD dst_unused:UNUSED_PAD src0_sel:DWORD src1_sel:WORD_1
	v_lshl_add_u64 v[40:41], v[160:161], 0, v[0:1]
	v_lshlrev_b32_e32 v0, 9, v37
	v_and_b32_e32 v0, 0x1fffe00, v0
	global_load_dwordx4 v[44:47], v[2:3], off
	global_load_dwordx4 v[48:51], v[40:41], off
	v_lshl_add_u64 v[2:3], v[160:161], 0, v[0:1]
	v_lshlrev_b32_sdwa v0, v171, v37 dst_sel:DWORD dst_unused:UNUSED_PAD src0_sel:DWORD src1_sel:WORD_1
	v_lshl_add_u64 v[36:37], v[160:161], 0, v[0:1]
	v_lshlrev_b32_e32 v0, 9, v38
	v_and_b32_e32 v0, 0x1fffe00, v0
	global_load_dwordx4 v[60:63], v[2:3], off
	global_load_dwordx4 v[68:71], v[36:37], off
	v_lshl_add_u64 v[2:3], v[160:161], 0, v[0:1]
	v_lshlrev_b32_sdwa v0, v171, v38 dst_sel:DWORD dst_unused:UNUSED_PAD src0_sel:DWORD src1_sel:WORD_1
	v_lshl_add_u64 v[36:37], v[160:161], 0, v[0:1]
	v_lshlrev_b32_e32 v0, 9, v39
	v_and_b32_e32 v0, 0x1fffe00, v0
	global_load_dwordx4 v[84:87], v[2:3], off
	global_load_dwordx4 v[88:91], v[36:37], off
	v_lshl_add_u64 v[2:3], v[160:161], 0, v[0:1]
	v_lshlrev_b32_sdwa v0, v171, v39 dst_sel:DWORD dst_unused:UNUSED_PAD src0_sel:DWORD src1_sel:WORD_1
	global_load_dwordx4 v[100:103], v[2:3], off
	v_lshl_add_u64 v[2:3], v[160:161], 0, v[0:1]
	global_load_dwordx4 v[108:111], v[2:3], off
.Lp4_skip0:
	s_add_i32 s28, s20, 1
	s_mul_i32 s29, s28, s89
	s_mul_i32 s30, s28, 37
	s_add_i32 s30, s30, s88
	v_readlane_b32 s31, v254, 32
	s_mul_hi_u32 s31, s30, s31
	v_readlane_b32 s33, v254, 33
	s_mul_i32 s31, s31, s33
	s_sub_i32 s30, s30, s31
	s_sub_i32 s31, s30, s33
	s_cmp_ge_u32 s30, s33
	s_cselect_b32 s30, s31, s30
	s_sub_i32 s31, s30, s33
	s_cmp_ge_u32 s30, s33
	s_cselect_b32 s30, s31, s30
	s_add_i32 s30, s30, s29
	s_cmpk_gt_i32 s29, 0x1fff
	s_cselect_b32 s30, s21, s30
	s_mov_b32 s36, s30
	s_lshl_b32 s30, s30, 11
	s_mov_b32 s31, 0
	v_lshl_add_u64 v[2:3], v[150:151], 0, s[30:31]
	global_load_dword v255, v[2:3], off
	s_waitcnt vmcnt(20)
	v_cvt_pk_f32_fp8_e32 v[202:203], v218
	v_cvt_pk_f32_fp8_sdwa v[204:205], v218 src0_sel:WORD_1
	v_cvt_pk_f32_fp8_e32 v[206:207], v219
	v_cvt_pk_f32_fp8_sdwa v[208:209], v219 src0_sel:WORD_1
	v_cvt_pk_bf16_f32 v4, v202, v203
	v_cvt_pk_bf16_f32 v5, v204, v205
	v_cvt_pk_bf16_f32 v6, v206, v207
	v_cvt_pk_bf16_f32 v7, v208, v209
	s_waitcnt vmcnt(19)
	v_cvt_pk_f32_fp8_e32 v[210:211], v220
	v_cvt_pk_f32_fp8_sdwa v[212:213], v220 src0_sel:WORD_1
	v_cvt_pk_f32_fp8_e32 v[214:215], v221
	v_cvt_pk_f32_fp8_sdwa v[216:217], v221 src0_sel:WORD_1
	v_cvt_pk_bf16_f32 v8, v210, v211
	v_cvt_pk_bf16_f32 v9, v212, v213
	v_cvt_pk_bf16_f32 v10, v214, v215
	v_cvt_pk_bf16_f32 v11, v216, v217
	s_waitcnt vmcnt(18)
	v_cvt_pk_f32_fp8_e32 v[202:203], v222
	v_cvt_pk_f32_fp8_sdwa v[204:205], v222 src0_sel:WORD_1
	v_cvt_pk_f32_fp8_e32 v[206:207], v223
	v_cvt_pk_f32_fp8_sdwa v[208:209], v223 src0_sel:WORD_1
	v_cvt_pk_bf16_f32 v12, v202, v203
	v_cvt_pk_bf16_f32 v13, v204, v205
	v_cvt_pk_bf16_f32 v14, v206, v207
	v_cvt_pk_bf16_f32 v15, v208, v209
	s_waitcnt vmcnt(17)
	v_cvt_pk_f32_fp8_e32 v[210:211], v224
	v_cvt_pk_f32_fp8_sdwa v[212:213], v224 src0_sel:WORD_1
	v_cvt_pk_f32_fp8_e32 v[214:215], v225
	v_cvt_pk_f32_fp8_sdwa v[216:217], v225 src0_sel:WORD_1
	v_cvt_pk_bf16_f32 v16, v210, v211
	v_cvt_pk_bf16_f32 v17, v212, v213
	v_cvt_pk_bf16_f32 v18, v214, v215
	v_cvt_pk_bf16_f32 v19, v216, v217
	s_waitcnt vmcnt(16)
	v_cvt_pk_f32_fp8_e32 v[202:203], v226
	v_cvt_pk_f32_fp8_sdwa v[204:205], v226 src0_sel:WORD_1
	v_cvt_pk_f32_fp8_e32 v[206:207], v227
	v_cvt_pk_f32_fp8_sdwa v[208:209], v227 src0_sel:WORD_1
	v_cvt_pk_bf16_f32 v20, v202, v203
	v_cvt_pk_bf16_f32 v21, v204, v205
	v_cvt_pk_bf16_f32 v22, v206, v207
	v_cvt_pk_bf16_f32 v23, v208, v209
	s_waitcnt vmcnt(15)
	v_cvt_pk_f32_fp8_e32 v[210:211], v228
	v_cvt_pk_f32_fp8_sdwa v[212:213], v228 src0_sel:WORD_1
	v_cvt_pk_f32_fp8_e32 v[214:215], v229
	v_cvt_pk_f32_fp8_sdwa v[216:217], v229 src0_sel:WORD_1
	v_cvt_pk_bf16_f32 v24, v210, v211
	v_cvt_pk_bf16_f32 v25, v212, v213
	v_cvt_pk_bf16_f32 v26, v214, v215
	v_cvt_pk_bf16_f32 v27, v216, v217
	s_waitcnt vmcnt(14)
	v_cvt_pk_f32_fp8_e32 v[202:203], v230
	v_cvt_pk_f32_fp8_sdwa v[204:205], v230 src0_sel:WORD_1
	v_cvt_pk_f32_fp8_e32 v[206:207], v231
	v_cvt_pk_f32_fp8_sdwa v[208:209], v231 src0_sel:WORD_1
	v_cvt_pk_bf16_f32 v28, v202, v203
	v_cvt_pk_bf16_f32 v29, v204, v205
	v_cvt_pk_bf16_f32 v30, v206, v207
	v_cvt_pk_bf16_f32 v31, v208, v209
	s_waitcnt vmcnt(13)
	v_cvt_pk_f32_fp8_e32 v[210:211], v232
	v_cvt_pk_f32_fp8_sdwa v[212:213], v232 src0_sel:WORD_1
	v_cvt_pk_f32_fp8_e32 v[214:215], v233
	v_cvt_pk_f32_fp8_sdwa v[216:217], v233 src0_sel:WORD_1
	v_cvt_pk_bf16_f32 v32, v210, v211
	v_cvt_pk_bf16_f32 v33, v212, v213
	v_cvt_pk_bf16_f32 v34, v214, v215
	v_cvt_pk_bf16_f32 v35, v216, v217
	s_and_b32 s14, s10, 0x7fc
	s_cmp_lt_u32 s14, 29
	s_cmp_lg_u32 s20, 0
	s_cbranch_scc1 .Lp4_w0b
	s_waitcnt vmcnt(8)
	ds_write_b128 v170, v[44:47]
	s_waitcnt vmcnt(7)
	ds_write_b128 v170, v[48:51] offset:544
	s_waitcnt vmcnt(6)
	ds_write_b128 v170, v[60:63] offset:1088
	s_waitcnt vmcnt(5)
	ds_write_b128 v170, v[68:71] offset:1632
	s_waitcnt vmcnt(4)
	ds_write_b128 v170, v[84:87] offset:2176
	s_waitcnt vmcnt(3)
	ds_write_b128 v170, v[88:91] offset:2720
	s_waitcnt vmcnt(2)
	ds_write_b128 v170, v[100:103] offset:3264
	s_waitcnt vmcnt(1)
	ds_write_b128 v170, v[108:111] offset:3808
	s_branch .Lp4_w0d
; #define P4_LOAD(ch) do { const u32x4 kk_ = *(const LAS u32x4*)(idxs + tok * 256 + (ch) * 32 + wrow); \
;       _Pragma("unroll") for (int i = 0; i < 8; ++i) { \
;       const int key = (int)((kk_[i >> 1] >> (16 * (i & 1))) & 0xffffu); stg[i] = *(const u32x4*)(cbase + (size_t)key * 256); } } while (0)
; #define P4_WRITE(bufp) do { _Pragma("unroll") for (int i = 0; i < 8; ++i) \
;       *(LAS u32x4*)((bufp) + (wrow + i) * CROW + 16 * (wch ^ (lane >> 5))) = stg[i]; } while (0)
; __device__ __forceinline__ void p4_attn(const Params& p, unsigned char* lds, int bid, int nb, bool dry) {
;     ...
;     P4_LOAD(0);
;     P4_WRITE(cbuf + tok * CTOK);
;     if (nch > 1) P4_LOAD(1);
.Lp4_w0b:
	s_waitcnt vmcnt(12)
	ds_write_b128 v170, v[44:47]
	s_waitcnt vmcnt(11)
	ds_write_b128 v170, v[48:51] offset:544
	s_waitcnt vmcnt(10)
	ds_write_b128 v170, v[60:63] offset:1088
	s_waitcnt vmcnt(9)
	ds_write_b128 v170, v[68:71] offset:1632
	s_waitcnt vmcnt(8)
	ds_write_b128 v170, v[84:87] offset:2176
	s_waitcnt vmcnt(7)
	ds_write_b128 v170, v[88:91] offset:2720
	s_waitcnt vmcnt(6)
	ds_write_b128 v170, v[100:103] offset:3264
	s_waitcnt vmcnt(5)
	ds_write_b128 v170, v[108:111] offset:3808
.Lp4_w0d:
	s_cmp_lt_u32 s14, 29
	s_cbranch_scc1 .LBB0_998
	ds_read_b128 v[36:39], v167 offset:64
	s_waitcnt lgkmcnt(0)
	v_lshlrev_b32_e32 v0, 9, v36
	v_and_b32_e32 v0, 0x1fffe00, v0
	v_lshl_add_u64 v[2:3], v[160:161], 0, v[0:1]
	v_lshlrev_b32_sdwa v0, v171, v36 dst_sel:DWORD dst_unused:UNUSED_PAD src0_sel:DWORD src1_sel:WORD_1
	v_lshl_add_u64 v[206:207], v[160:161], 0, v[0:1]
	global_load_dwordx4 v[202:205], v[2:3], off
	global_load_dwordx4 v[206:209], v[206:207], off
	v_lshlrev_b32_e32 v0, 9, v37
	v_and_b32_e32 v0, 0x1fffe00, v0
	v_lshl_add_u64 v[2:3], v[160:161], 0, v[0:1]
	v_lshlrev_b32_sdwa v0, v171, v37 dst_sel:DWORD dst_unused:UNUSED_PAD src0_sel:DWORD src1_sel:WORD_1
	v_lshl_add_u64 v[214:215], v[160:161], 0, v[0:1]
	global_load_dwordx4 v[210:213], v[2:3], off
	global_load_dwordx4 v[214:217], v[214:215], off
	v_lshlrev_b32_e32 v0, 9, v38
	v_and_b32_e32 v0, 0x1fffe00, v0
	v_lshl_add_u64 v[2:3], v[160:161], 0, v[0:1]
	v_lshlrev_b32_sdwa v0, v171, v38 dst_sel:DWORD dst_unused:UNUSED_PAD src0_sel:DWORD src1_sel:WORD_1
	v_lshl_add_u64 v[222:223], v[160:161], 0, v[0:1]
	global_load_dwordx4 v[218:221], v[2:3], off
	global_load_dwordx4 v[222:225], v[222:223], off
	v_lshlrev_b32_e32 v0, 9, v39
	v_and_b32_e32 v0, 0x1fffe00, v0
	v_lshl_add_u64 v[2:3], v[160:161], 0, v[0:1]
	v_lshlrev_b32_sdwa v0, v171, v39 dst_sel:DWORD dst_unused:UNUSED_PAD src0_sel:DWORD src1_sel:WORD_1
	v_lshl_add_u64 v[230:231], v[160:161], 0, v[0:1]
	global_load_dwordx4 v[226:229], v[2:3], off
	global_load_dwordx4 v[230:233], v[230:231], off
	s_cmp_lt_u32 s14, 61
	s_cbranch_scc1 .LBB0_998
	ds_read_b128 v[36:39], v167 offset:128
	s_waitcnt lgkmcnt(0)
	v_lshlrev_b32_e32 v0, 9, v36
	v_and_b32_e32 v0, 0x1fffe00, v0
	v_lshl_add_u64 v[2:3], v[160:161], 0, v[0:1]
	v_lshlrev_b32_sdwa v0, v171, v36 dst_sel:DWORD dst_unused:UNUSED_PAD src0_sel:DWORD src1_sel:WORD_1
	v_lshl_add_u64 v[48:49], v[160:161], 0, v[0:1]
	global_load_dwordx4 v[44:47], v[2:3], off
	global_load_dwordx4 v[48:51], v[48:49], off
	v_lshlrev_b32_e32 v0, 9, v37
	v_and_b32_e32 v0, 0x1fffe00, v0
	v_lshl_add_u64 v[2:3], v[160:161], 0, v[0:1]
	v_lshlrev_b32_sdwa v0, v171, v37 dst_sel:DWORD dst_unused:UNUSED_PAD src0_sel:DWORD src1_sel:WORD_1
	v_lshl_add_u64 v[68:69], v[160:161], 0, v[0:1]
	global_load_dwordx4 v[60:63], v[2:3], off
	global_load_dwordx4 v[68:71], v[68:69], off
	v_lshlrev_b32_e32 v0, 9, v38
	v_and_b32_e32 v0, 0x1fffe00, v0
	v_lshl_add_u64 v[2:3], v[160:161], 0, v[0:1]
	v_lshlrev_b32_sdwa v0, v171, v38 dst_sel:DWORD dst_unused:UNUSED_PAD src0_sel:DWORD src1_sel:WORD_1
	v_lshl_add_u64 v[88:89], v[160:161], 0, v[0:1]
	global_load_dwordx4 v[84:87], v[2:3], off
	global_load_dwordx4 v[88:91], v[88:89], off
	v_lshlrev_b32_e32 v0, 9, v39
	v_and_b32_e32 v0, 0x1fffe00, v0
	v_lshl_add_u64 v[2:3], v[160:161], 0, v[0:1]
	v_lshlrev_b32_sdwa v0, v171, v39 dst_sel:DWORD dst_unused:UNUSED_PAD src0_sel:DWORD src1_sel:WORD_1
	v_lshl_add_u64 v[108:109], v[160:161], 0, v[0:1]
	global_load_dwordx4 v[100:103], v[2:3], off
	global_load_dwordx4 v[108:111], v[108:109], off

; #define LAS __attribute__((address_space(3)))
; #define P4_LOAD(ch) do { const u32x4 kk_ = *(const LAS u32x4*)(idxs + tok * 256 + (ch) * 32 + wrow); \
;       _Pragma("unroll") for (int i = 0; i < 8; ++i) { \
;       const int key = (int)((kk_[i >> 1] >> (16 * (i & 1))) & 0xffffu); stg[i] = *(const u32x4*)(cbase + (size_t)key * 256); } } while (0)
; #define P4_WRITE(bufp) do { _Pragma("unroll") for (int i = 0; i < 8; ++i) \
;       *(LAS u32x4*)((bufp) + (wrow + i) * CROW + 16 * (wch ^ (lane >> 5))) = stg[i]; } while (0)
; __device__ __forceinline__ void p4_attn(const Params& p, unsigned char* lds, int bid, int nb, bool dry) {
;     ...
;     ((LAS unsigned*)idxs)[tid] = ((const unsigned*)(idxg + (size_t)tg0 * 256))[tid];
;     unsigned char* qrow = QL + (size_t)tg * 8192 + head * 256;
;     bf16x8 qB[8];
; #pragma unroll
;     for (int s = 0; s < 8; ++s) { const u32x2 qw = *(const u32x2*)(qrow + 32 * s + 8 * g);
;     ...
;     for (int ch = 0; ch < nch; ++ch) {
;       LAS unsigned char* cb = cbuf + (ch & 1) * CBUF + tok * CTOK;
;       if (ch + 1 < nch) { P4_WRITE(cbuf + ((ch + 1) & 1) * CBUF + tok * CTOK); if (ch + 2 < nch) P4_LOAD(ch + 2); }
;       f32x4 s0 = (f32x4){0.f, 0.f, 0.f, 0.f}, s1 = (f32x4){0.f, 0.f, 0.f, 0.f};
; #pragma unroll
;       for (int s = 0; s < 8; ++s) {
;         const bf16x8 a0 = *(const LAS bf16x8*)(cb + r16 * CROW + s * 64 + qoff);
;         const bf16x8 a1 = *(const LAS bf16x8*)(cb + (16 + r16) * CROW + s * 64 + qoff);
;         s0 = __builtin_amdgcn_mfma_f32_16x16x32_bf16(a0, qB[s], s0, 0, 0, 0);
;         s1 = __builtin_amdgcn_mfma_f32_16x16x32_bf16(a1, qB[s], s1, 0, 0, 0);
;       }
;       const int slotb = ch * 32 + 4 * g;
;       const u32x2 k0 = *(const LAS u32x2*)(idxs + tok * 256 + slotb), k1 = *(const LAS u32x2*)(idxs + tok * 256 + slotb + 16);
.LBB0_1007:
	s_lshl_b32 s37, s36, 2
	s_add_i32 s37, s37, s0
	s_lshl_b32 s38, s37, 13
	s_mov_b32 s39, 0
	v_lshl_add_u64 v[194:195], v[152:153], 0, s[38:39]
	v_lshl_add_u64 v[194:195], v[194:195], 0, v[154:155]
	global_load_dwordx2 v[218:219], v[194:195], off
	global_load_dwordx2 v[220:221], v[194:195], off offset:32
	global_load_dwordx2 v[222:223], v[194:195], off offset:64
	global_load_dwordx2 v[224:225], v[194:195], off offset:96
	global_load_dwordx2 v[226:227], v[194:195], off offset:128
	global_load_dwordx2 v[228:229], v[194:195], off offset:160
	global_load_dwordx2 v[230:231], v[194:195], off offset:192
	global_load_dwordx2 v[232:233], v[194:195], off offset:224
	s_waitcnt vmcnt(8)
	v_and_b32_e32 v194, 63, v200
	v_lshl_add_u32 v194, v194, 2, s42
	s_and_saveexec_b64 s[46:47], s[40:41]
	s_cbranch_execz .Lp4_noscr
	ds_write_b32 v194, v255
.Lp4_noscr:
	s_mov_b64 exec, s[46:47]
	s_bitcmp1_b32 s10, 0
	s_cselect_b32 s11, 0x11000, 0
	s_add_i32 s12, s5, s11
	s_lshl_b32 s13, s10, 5
	v_add3_u32 v2, s12, v168, v162
	ds_read_b128 v[234:237], v2
	ds_read_b128 v[238:241], v2 offset:8704
	ds_read_b128 v[242:245], v2 offset:64
	ds_read_b128 v[246:249], v2 offset:8768
	ds_read_b128 v[250:253], v2 offset:128
	ds_read_b128 v[188:191], v2 offset:8832
	v_or_b32_e32 v0, s13, v148
	v_lshl_add_u32 v3, v0, 1, s3
	s_waitcnt lgkmcnt(5)
	v_mfma_f32_16x16x32_bf16 v[140:143], v[234:237], v[4:7], 0
	ds_read_b128 v[234:237], v2 offset:192
	s_waitcnt lgkmcnt(5)
	v_mfma_f32_16x16x32_bf16 v[144:147], v[238:241], v[4:7], 0
	ds_read_b128 v[238:241], v2 offset:8896
	ds_read2_b64 v[184:187], v3 offset1:4
	s_waitcnt lgkmcnt(6)
	v_mfma_f32_16x16x32_bf16 v[140:143], v[242:245], v[8:11], v[140:143]
	ds_read_b128 v[242:245], v2 offset:256
	s_waitcnt lgkmcnt(6)
	v_mfma_f32_16x16x32_bf16 v[144:147], v[246:249], v[8:11], v[144:147]
	ds_read_b128 v[246:249], v2 offset:8960
	s_waitcnt lgkmcnt(6)
	v_mfma_f32_16x16x32_bf16 v[140:143], v[250:253], v[12:15], v[140:143]
	ds_read_b128 v[250:253], v2 offset:320
	s_waitcnt lgkmcnt(6)
	v_mfma_f32_16x16x32_bf16 v[144:147], v[188:191], v[12:15], v[144:147]
	ds_read_b128 v[188:191], v2 offset:9024
	s_waitcnt lgkmcnt(6)
	v_mfma_f32_16x16x32_bf16 v[140:143], v[234:237], v[16:19], v[140:143]
	ds_read_b128 v[234:237], v2 offset:384
	s_waitcnt lgkmcnt(6)
	v_mfma_f32_16x16x32_bf16 v[144:147], v[238:241], v[16:19], v[144:147]
	ds_read_b128 v[238:241], v2 offset:9088
	s_waitcnt lgkmcnt(5)
	v_mfma_f32_16x16x32_bf16 v[140:143], v[242:245], v[20:23], v[140:143]
	ds_read_b128 v[242:245], v2 offset:448
	s_waitcnt lgkmcnt(5)
	v_mfma_f32_16x16x32_bf16 v[144:147], v[246:249], v[20:23], v[144:147]
	ds_read_b128 v[246:249], v2 offset:9152
	s_waitcnt lgkmcnt(5)
	v_mfma_f32_16x16x32_bf16 v[140:143], v[250:253], v[24:27], v[140:143]
	s_waitcnt lgkmcnt(4)
	v_mfma_f32_16x16x32_bf16 v[144:147], v[188:191], v[24:27], v[144:147]
	s_waitcnt lgkmcnt(3)
	v_mfma_f32_16x16x32_bf16 v[140:143], v[234:237], v[28:31], v[140:143]
	s_waitcnt lgkmcnt(2)
	v_mfma_f32_16x16x32_bf16 v[144:147], v[238:241], v[28:31], v[144:147]
	s_waitcnt lgkmcnt(1)
	v_mfma_f32_16x16x32_bf16 v[140:143], v[242:245], v[32:35], v[140:143]
	s_waitcnt lgkmcnt(0)
	v_mfma_f32_16x16x32_bf16 v[144:147], v[246:249], v[32:35], v[144:147]
	s_branch .Lp4_softmax

; #define LAS __attribute__((address_space(3)))
; __device__ __forceinline__ u32x4 pack8(f32x4 a, f32x4 b) { u32x4 w; w[0] = cvt_pk_bf16(a[0], a[1]); w[1] = cvt_pk_bf16(a[2], a[3]); w[2] = cvt_pk_bf16(b[0], b[1]); w[3] = cvt_pk_bf16(b[2], b[3]); return w; }
; __device__ __forceinline__ float psum16(float x) { const u32x2s r = __builtin_amdgcn_permlane16_swap(__float_as_uint(x), __float_as_uint(x), false, false); return __uint_as_float(r[0]) + __uint_as_float(r[1]); }
; __device__ __forceinline__ float psum32(float x) { const u32x2s r = __builtin_amdgcn_permlane32_swap(__float_as_uint(x), __float_as_uint(x), false, false); return __uint_as_float(r[0]) + __uint_as_float(r[1]); }
; __device__ __forceinline__ void p4_attn(const Params& p, unsigned char* lds, int bid, int nb, bool dry) {
;     ...
;       for (int i = 0; i < 4; ++i) { p0[i] = __builtin_amdgcn_exp2f(lg0[i] - m_run); p1[i] = __builtin_amdgcn_exp2f(lg1[i] - m_run); ps += p0[i] + p1[i]; }
;       l_run = l_run * alpha + ps;
;       const u32x4 pw = pack8(p0, p1);
;       bf16x8 pb; { union { u32x4 u; bf16x8 v; } cv; cv.u = pw; pb = cv.v; }
;       LAS unsigned char* trb = cb + troff;
; #pragma unroll
;       for (int ct = 0; ct < 16; ++ct) {
;         const s16x4 ta = __builtin_amdgcn_ds_read_tr16_b64_v4i16((LAS s16x4*)(trb + 32 * ct));
;         const s16x4 tb = __builtin_amdgcn_ds_read_tr16_b64_v4i16((LAS s16x4*)(trb + 16 * CROW + 32 * ct));
;         const bf16x8 a = {ta[0], ta[1], ta[2], ta[3], tb[0], tb[1], tb[2], tb[3]};
;         o[ct] = __builtin_amdgcn_mfma_f32_16x16x32_bf16(a, pb, o[ct], 0, 0, 0);
;       }
;       epoch += 2u; pair_sync(pcnt, epoch, lane);
;     }
;     const float l = psum32(psum16(l_run));
;     const float inv = 16.f / l;
;     unsigned char* orow = qrow + 4 * g;
; #pragma unroll
;     for (int ct = 0; ct < 16; ++ct) {
;       unsigned w = __builtin_amdgcn_cvt_pk_fp8_f32(o[ct][0] * inv, o[ct][1] * inv, 0, false); w = __builtin_amdgcn_cvt_pk_fp8_f32(o[ct][2] * inv, o[ct][3] * inv, w, true);
;       if (!dry) *(unsigned*)(orow + 16 * ct) = w;
;     }
.LBB0_1019:
	v_add_f32_e32 v2, v2, v3
	v_add_f32_e32 v3, v132, v133
	v_add_f32_e32 v2, 0, v2
	v_add_f32_e32 v132, v134, v136
	v_add_f32_e32 v2, v3, v2
	v_add_f32_e32 v133, v135, v137
	v_add_f32_e32 v2, v132, v2
	v_add_f32_e32 v2, v133, v2
	v_fmac_f32_e32 v2, v174, v0
	s_cmp_eq_u32 s23, s22
	s_cbranch_scc0 .LBB0_1004
	v_add_u32_e32 v202, s44, v167
	ds_read_b128 v[202:205], v202
	s_ashr_i32 s46, s36, 9
	s_ashr_i32 s47, s46, 31
	s_lshl_b64 s[46:47], s[46:47], 20
	v_lshl_add_u64 v[210:211], v[156:157], 0, s[46:47]
	v_mov_b32_e32 v207, 0
	s_waitcnt lgkmcnt(0)
	v_lshlrev_b32_e32 v206, 9, v202
	v_and_b32_e32 v206, 0x1fffe00, v206
	v_lshl_add_u64 v[208:209], v[210:211], 0, v[206:207]
	v_lshlrev_b32_sdwa v206, v171, v202 dst_sel:DWORD dst_unused:UNUSED_PAD src0_sel:DWORD src1_sel:WORD_1
	v_lshl_add_u64 v[48:49], v[210:211], 0, v[206:207]
	global_load_dwordx4 v[44:47], v[208:209], off
	global_load_dwordx4 v[48:51], v[48:49], off
	v_lshlrev_b32_e32 v206, 9, v203
	v_and_b32_e32 v206, 0x1fffe00, v206
	v_lshl_add_u64 v[208:209], v[210:211], 0, v[206:207]
	v_lshlrev_b32_sdwa v206, v171, v203 dst_sel:DWORD dst_unused:UNUSED_PAD src0_sel:DWORD src1_sel:WORD_1
	v_lshl_add_u64 v[68:69], v[210:211], 0, v[206:207]
	global_load_dwordx4 v[60:63], v[208:209], off
	global_load_dwordx4 v[68:71], v[68:69], off
	v_lshlrev_b32_e32 v206, 9, v204
	v_and_b32_e32 v206, 0x1fffe00, v206
	v_lshl_add_u64 v[208:209], v[210:211], 0, v[206:207]
	v_lshlrev_b32_sdwa v206, v171, v204 dst_sel:DWORD dst_unused:UNUSED_PAD src0_sel:DWORD src1_sel:WORD_1
	v_lshl_add_u64 v[88:89], v[210:211], 0, v[206:207]
	global_load_dwordx4 v[84:87], v[208:209], off
	global_load_dwordx4 v[88:91], v[88:89], off
	v_lshlrev_b32_e32 v206, 9, v205
	v_and_b32_e32 v206, 0x1fffe00, v206
	v_lshl_add_u64 v[208:209], v[210:211], 0, v[206:207]
	v_lshlrev_b32_sdwa v206, v171, v205 dst_sel:DWORD dst_unused:UNUSED_PAD src0_sel:DWORD src1_sel:WORD_1
	v_lshl_add_u64 v[108:109], v[210:211], 0, v[206:207]
	global_load_dwordx4 v[100:103], v[208:209], off
	global_load_dwordx4 v[108:111], v[108:109], off
	v_mov_b32_e32 v0, v2
	s_nop 1
	v_permlane16_swap_b32_e32 v2, v0
	v_add_f32_e32 v0, v2, v0
	v_mov_b32_e32 v2, v0
	s_nop 1
	v_permlane32_swap_b32_e32 v0, v2
	v_add_f32_e32 v0, v0, v2
	v_div_scale_f32 v2, s[10:11], v0, v0, s18
	v_rcp_f32_e32 v3, v2
	v_mov_b32_e32 v7, v1
	s_add_i32 s20, s20, 1
	s_mul_i32 s10, s20, s89
	v_fma_f32 v4, -v2, v3, 1.0
	v_fmac_f32_e32 v3, v4, v3
	v_div_scale_f32 v4, vcc, s18, v0, s18
	v_mul_f32_e32 v5, v4, v3
	v_fma_f32 v6, -v2, v5, v4
	v_fmac_f32_e32 v5, v6, v3
	v_fma_f32 v2, -v2, v5, v4
	v_div_fmas_f32 v2, v2, v3, v5
	v_div_fixup_f32 v0, v2, v0, s18
	v_mul_f32_e32 v20, v128, v0
	v_mul_f32_e32 v21, v129, v0
	v_mov_b32_e32 v4, v1
	v_cvt_pk_fp8_f32 v4, v20, v21
	v_mul_f32_e32 v22, v130, v0
	v_mul_f32_e32 v23, v131, v0
	v_cvt_pk_fp8_f32 v4, v22, v23 op_sel:[0,0,1]
	v_mul_f32_e32 v20, v124, v0
	v_mul_f32_e32 v21, v125, v0
	v_mov_b32_e32 v5, v1
	v_cvt_pk_fp8_f32 v5, v20, v21
	v_mul_f32_e32 v22, v126, v0
	v_mul_f32_e32 v23, v127, v0
	v_cvt_pk_fp8_f32 v5, v22, v23 op_sel:[0,0,1]
	v_mul_f32_e32 v20, v120, v0
	v_mul_f32_e32 v21, v121, v0
	v_mov_b32_e32 v6, v1
	v_cvt_pk_fp8_f32 v6, v20, v21
	v_mul_f32_e32 v22, v122, v0
	v_mul_f32_e32 v23, v123, v0
	v_cvt_pk_fp8_f32 v6, v22, v23 op_sel:[0,0,1]
	v_mul_f32_e32 v20, v116, v0
	v_mul_f32_e32 v21, v117, v0
	v_mov_b32_e32 v7, v1
	v_cvt_pk_fp8_f32 v7, v20, v21
	v_mul_f32_e32 v22, v118, v0
	v_mul_f32_e32 v23, v119, v0
	v_cvt_pk_fp8_f32 v7, v22, v23 op_sel:[0,0,1]
	v_mul_f32_e32 v20, v112, v0
	v_mul_f32_e32 v21, v113, v0
	v_mov_b32_e32 v8, v1
	v_cvt_pk_fp8_f32 v8, v20, v21
	v_mul_f32_e32 v22, v114, v0
	v_mul_f32_e32 v23, v115, v0
	v_cvt_pk_fp8_f32 v8, v22, v23 op_sel:[0,0,1]
	v_mul_f32_e32 v20, v104, v0
	v_mul_f32_e32 v21, v105, v0
	v_mov_b32_e32 v9, v1
	v_cvt_pk_fp8_f32 v9, v20, v21
	v_mul_f32_e32 v22, v106, v0
	v_mul_f32_e32 v23, v107, v0
	v_cvt_pk_fp8_f32 v9, v22, v23 op_sel:[0,0,1]
	v_mul_f32_e32 v20, v96, v0
	v_mul_f32_e32 v21, v97, v0
	v_mov_b32_e32 v10, v1
	v_cvt_pk_fp8_f32 v10, v20, v21
	v_mul_f32_e32 v22, v98, v0
	v_mul_f32_e32 v23, v99, v0
	v_cvt_pk_fp8_f32 v10, v22, v23 op_sel:[0,0,1]
	v_mul_f32_e32 v20, v92, v0
	v_mul_f32_e32 v21, v93, v0
	v_mov_b32_e32 v11, v1
	v_cvt_pk_fp8_f32 v11, v20, v21
	v_mul_f32_e32 v22, v94, v0
	v_mul_f32_e32 v23, v95, v0
	v_cvt_pk_fp8_f32 v11, v22, v23 op_sel:[0,0,1]
	v_mul_f32_e32 v20, v80, v0
	v_mul_f32_e32 v21, v81, v0
	v_mov_b32_e32 v12, v1
	v_cvt_pk_fp8_f32 v12, v20, v21
	v_mul_f32_e32 v22, v82, v0
	v_mul_f32_e32 v23, v83, v0
	v_cvt_pk_fp8_f32 v12, v22, v23 op_sel:[0,0,1]
	v_mul_f32_e32 v20, v76, v0
	v_mul_f32_e32 v21, v77, v0
	v_mov_b32_e32 v13, v1
	v_cvt_pk_fp8_f32 v13, v20, v21
	v_mul_f32_e32 v22, v78, v0
	v_mul_f32_e32 v23, v79, v0
	v_cvt_pk_fp8_f32 v13, v22, v23 op_sel:[0,0,1]
	v_mul_f32_e32 v20, v72, v0
	v_mul_f32_e32 v21, v73, v0
	v_mov_b32_e32 v14, v1
	v_cvt_pk_fp8_f32 v14, v20, v21
	v_mul_f32_e32 v22, v74, v0
	v_mul_f32_e32 v23, v75, v0
	v_cvt_pk_fp8_f32 v14, v22, v23 op_sel:[0,0,1]
	v_mul_f32_e32 v20, v64, v0
	v_mul_f32_e32 v21, v65, v0
	v_mov_b32_e32 v15, v1
	v_cvt_pk_fp8_f32 v15, v20, v21
	v_mul_f32_e32 v22, v66, v0
	v_mul_f32_e32 v23, v67, v0
	v_cvt_pk_fp8_f32 v15, v22, v23 op_sel:[0,0,1]
	v_mul_f32_e32 v20, v56, v0
	v_mul_f32_e32 v21, v57, v0
	v_mov_b32_e32 v16, v1
	v_cvt_pk_fp8_f32 v16, v20, v21
	v_mul_f32_e32 v22, v58, v0
	v_mul_f32_e32 v23, v59, v0
	v_cvt_pk_fp8_f32 v16, v22, v23 op_sel:[0,0,1]
	v_mul_f32_e32 v20, v52, v0
	v_mul_f32_e32 v21, v53, v0
	v_mov_b32_e32 v17, v1
	v_cvt_pk_fp8_f32 v17, v20, v21
	v_mul_f32_e32 v22, v54, v0
	v_mul_f32_e32 v23, v55, v0
	v_cvt_pk_fp8_f32 v17, v22, v23 op_sel:[0,0,1]
	v_mul_f32_e32 v20, v40, v0
	v_mul_f32_e32 v21, v41, v0
	v_mov_b32_e32 v18, v1
	v_cvt_pk_fp8_f32 v18, v20, v21
	v_mul_f32_e32 v22, v42, v0
	v_mul_f32_e32 v23, v43, v0
	v_cvt_pk_fp8_f32 v18, v22, v23 op_sel:[0,0,1]
	v_mul_f32_e32 v20, v36, v0
	v_mul_f32_e32 v21, v37, v0
	v_mov_b32_e32 v19, v1
	v_cvt_pk_fp8_f32 v19, v20, v21
	v_mul_f32_e32 v22, v38, v0
	v_mul_f32_e32 v23, v39, v0
	v_cvt_pk_fp8_f32 v19, v22, v23 op_sel:[0,0,1]
	v_lshlrev_b32_e32 v24, 2, v148
	v_mov_b32_e32 v25, 0
	v_lshl_add_u64 v[24:25], v[158:159], 0, v[24:25]
	s_add_i32 s1, s1, s89
	s_cmpk_gt_i32 s10, 0x1fff
	s_nop 1
	v_permlane32_swap_b32_e32 v4, v6
	v_permlane32_swap_b32_e32 v5, v7
	v_permlane32_swap_b32_e32 v8, v10
	v_permlane32_swap_b32_e32 v9, v11
	v_permlane32_swap_b32_e32 v12, v14
	v_permlane32_swap_b32_e32 v13, v15
	v_permlane32_swap_b32_e32 v16, v18
	v_permlane32_swap_b32_e32 v17, v19
	v_permlane16_swap_b32_e32 v4, v5
	v_permlane16_swap_b32_e32 v6, v7
	v_permlane16_swap_b32_e32 v8, v9
	v_permlane16_swap_b32_e32 v10, v11
	v_permlane16_swap_b32_e32 v12, v13
	v_permlane16_swap_b32_e32 v14, v15
	v_permlane16_swap_b32_e32 v16, v17
	v_permlane16_swap_b32_e32 v18, v19
	s_nop 1
	global_store_dwordx4 v[24:25], v[4:7], off
	global_store_dwordx4 v[24:25], v[8:11], off offset:64
	global_store_dwordx4 v[24:25], v[12:15], off offset:128
	global_store_dwordx4 v[24:25], v[16:19], off offset:192
	s_cbranch_scc0 .LBB0_991
; __device__ __forceinline__ void grid_bar(unsigned* ctr, unsigned target) {
;   __syncthreads();
;   if (threadIdx.x == 0) {
;     __builtin_amdgcn_fence(__ATOMIC_RELEASE, "agent");
;     asm volatile("s_waitcnt vmcnt(0)" ::: "memory");
;     __hip_atomic_fetch_add(ctr, 1u, __ATOMIC_RELAXED, __HIP_MEMORY_SCOPE_AGENT);
;     while (__hip_atomic_load(ctr, __ATOMIC_RELAXED, __HIP_MEMORY_SCOPE_AGENT) < target) __builtin_amdgcn_s_sleep(2);
; __global__ void __launch_bounds__(512, 2) fwd_mega(Params p) {
;     ...
;   REPS(4) { p4_attn(p, lds, bid, nb, DRY); __syncthreads(); }
;   grid_bar(bar, (unsigned)(3 * nb));
	s_barrier
	s_barrier
	s_mov_b64 s[4:5], exec
	v_readlane_b32 s0, v254, 44
	v_readlane_b32 s1, v254, 45
	s_and_b64 s[0:1], s[4:5], s[0:1]
	s_mov_b64 exec, s[0:1]
	s_cbranch_execz .LBB0_1028
	s_mov_b64 s[8:9], exec
	buffer_wbl2 sc1
	s_waitcnt vmcnt(0)
	s_waitcnt vmcnt(0)
	v_mbcnt_lo_u32_b32 v0, s8, 0
	v_mbcnt_hi_u32_b32 v0, s9, v0
	v_cmp_eq_u32_e32 vcc, 0, v0
	s_and_saveexec_b64 s[10:11], vcc
	s_cbranch_execz .LBB0_1024
	s_bcnt1_i32_b64 s0, s[8:9]
	v_mov_b32_e32 v1, s0
	v_readlane_b32 s0, v254, 20
	v_mov_b32_e32 v0, 0
	v_readlane_b32 s1, v254, 21
	s_nop 4
	global_atomic_add v0, v1, s[0:1]
